# G2 residual epilogue rewritten by hand (f32-base path with rolling 16-load prefetch, bf16 path all loads up front); old serialized body deleted
# baseline (speedup 1.0000x reference)
.LBB0_815:
	s_and_b64 vcc, exec, s[28:29]
	s_cbranch_vccz .Lg2_epi_bf16
	v_lshl_add_u32 v238, s77, 8, v174
	v_lshl_or_b32 v237, s76, 8, v176
	v_lshl_add_u32 v237, v238, 10, v237
	v_lshlrev_b32_e32 v236, 2, v237
	v_lshlrev_b32_e32 v237, 1, v237
	v_lshlrev_b32_e32 v238, 2, v238
	global_load_dwordx4 v[132:135], v236, s[6:7]
	global_load_dwordx4 v[136:139], v236, s[6:7] offset:16
	global_load_dwordx4 v[148:151], v236, s[6:7] offset:512
	global_load_dwordx4 v[152:155], v236, s[6:7] offset:528
	v_add_u32_e32 v236, 0x10000, v236
	global_load_dwordx4 v[178:181], v236, s[6:7]
	global_load_dwordx4 v[182:185], v236, s[6:7] offset:16
	global_load_dwordx4 v[186:189], v236, s[6:7] offset:512
	global_load_dwordx4 v[190:193], v236, s[6:7] offset:528
	v_add_u32_e32 v236, 0x10000, v236
	global_load_dwordx4 v[200:203], v236, s[6:7]
	global_load_dwordx4 v[204:207], v236, s[6:7] offset:16
	global_load_dwordx4 v[208:211], v236, s[6:7] offset:512
	global_load_dwordx4 v[212:215], v236, s[6:7] offset:528
	v_add_u32_e32 v236, 0x10000, v236
	global_load_dwordx4 v[216:219], v236, s[6:7]
	global_load_dwordx4 v[220:223], v236, s[6:7] offset:16
	global_load_dwordx4 v[224:227], v236, s[6:7] offset:512
	global_load_dwordx4 v[228:231], v236, s[6:7] offset:528
	v_add_u32_e32 v236, 0x50000, v236
	v_xor_b32_e32 v239, 16, v197
	v_xor_b32_e32 v172, 32, v197
	v_lshlrev_b32_e32 v239, 2, v239
	v_lshlrev_b32_e32 v172, 2, v172
	s_waitcnt vmcnt(12)
	v_pk_add_f32 v[128:129], v[128:129], v[132:133]
	v_pk_add_f32 v[130:131], v[130:131], v[134:135]
	v_pk_add_f32 v[124:125], v[124:125], v[136:137]
	v_pk_add_f32 v[126:127], v[126:127], v[138:139]
	v_cvt_pk_bf16_f32 v132, v128, v129
	v_cvt_pk_bf16_f32 v133, v130, v131
	v_cvt_pk_bf16_f32 v134, v124, v125
	v_cvt_pk_bf16_f32 v135, v126, v127
	global_store_dwordx4 v237, v[132:135], s[8:9]
	v_pk_mul_f32 v[128:129], v[128:129], v[128:129]
	v_pk_mul_f32 v[130:131], v[130:131], v[130:131]
	v_pk_fma_f32 v[128:129], v[124:125], v[124:125], v[128:129]
	v_pk_fma_f32 v[130:131], v[126:127], v[126:127], v[130:131]
	v_pk_add_f32 v[120:121], v[120:121], v[148:149]
	v_pk_add_f32 v[122:123], v[122:123], v[150:151]
	v_pk_add_f32 v[116:117], v[116:117], v[152:153]
	v_pk_add_f32 v[118:119], v[118:119], v[154:155]
	v_cvt_pk_bf16_f32 v148, v120, v121
	v_cvt_pk_bf16_f32 v149, v122, v123
	v_cvt_pk_bf16_f32 v150, v116, v117
	v_cvt_pk_bf16_f32 v151, v118, v119
	global_store_dwordx4 v237, v[148:151], s[8:9] offset:256
	v_pk_fma_f32 v[128:129], v[120:121], v[120:121], v[128:129]
	v_pk_fma_f32 v[130:131], v[122:123], v[122:123], v[130:131]
	v_pk_fma_f32 v[128:129], v[116:117], v[116:117], v[128:129]
	v_pk_fma_f32 v[130:131], v[118:119], v[118:119], v[130:131]
	v_add_u32_e32 v237, 0x8000, v237
	v_add_f32_e32 v128, v128, v129
	v_add_f32_e32 v130, v130, v131
	v_add_f32_e32 v128, v128, v130
	global_load_dwordx4 v[132:135], v236, s[6:7]
	global_load_dwordx4 v[136:139], v236, s[6:7] offset:16
	global_load_dwordx4 v[148:151], v236, s[6:7] offset:512
	global_load_dwordx4 v[152:155], v236, s[6:7] offset:528
	v_add_u32_e32 v236, 0x10000, v236
	s_waitcnt vmcnt(14)
	v_pk_add_f32 v[112:113], v[112:113], v[178:179]
	v_pk_add_f32 v[114:115], v[114:115], v[180:181]
	v_pk_add_f32 v[108:109], v[108:109], v[182:183]
	v_pk_add_f32 v[110:111], v[110:111], v[184:185]
	v_cvt_pk_bf16_f32 v178, v112, v113
	v_cvt_pk_bf16_f32 v179, v114, v115
	v_cvt_pk_bf16_f32 v180, v108, v109
	v_cvt_pk_bf16_f32 v181, v110, v111
	global_store_dwordx4 v237, v[178:181], s[8:9]
	v_pk_mul_f32 v[112:113], v[112:113], v[112:113]
	v_pk_mul_f32 v[114:115], v[114:115], v[114:115]
	v_pk_fma_f32 v[112:113], v[108:109], v[108:109], v[112:113]
	v_pk_fma_f32 v[114:115], v[110:111], v[110:111], v[114:115]
	v_pk_add_f32 v[104:105], v[104:105], v[186:187]
	v_pk_add_f32 v[106:107], v[106:107], v[188:189]
	v_pk_add_f32 v[100:101], v[100:101], v[190:191]
	v_pk_add_f32 v[102:103], v[102:103], v[192:193]
	v_cvt_pk_bf16_f32 v186, v104, v105
	v_cvt_pk_bf16_f32 v187, v106, v107
	v_cvt_pk_bf16_f32 v188, v100, v101
	v_cvt_pk_bf16_f32 v189, v102, v103
	global_store_dwordx4 v237, v[186:189], s[8:9] offset:256
	v_pk_fma_f32 v[112:113], v[104:105], v[104:105], v[112:113]
	v_pk_fma_f32 v[114:115], v[106:107], v[106:107], v[114:115]
	v_pk_fma_f32 v[112:113], v[100:101], v[100:101], v[112:113]
	v_pk_fma_f32 v[114:115], v[102:103], v[102:103], v[114:115]
	v_add_u32_e32 v237, 0x8000, v237
	v_add_f32_e32 v112, v112, v113
	v_add_f32_e32 v114, v114, v115
	v_add_f32_e32 v112, v112, v114
	global_load_dwordx4 v[178:181], v236, s[6:7]
	global_load_dwordx4 v[182:185], v236, s[6:7] offset:16
	global_load_dwordx4 v[186:189], v236, s[6:7] offset:512
	global_load_dwordx4 v[190:193], v236, s[6:7] offset:528
	v_add_u32_e32 v236, 0x10000, v236
	s_waitcnt vmcnt(16)
	v_pk_add_f32 v[96:97], v[96:97], v[200:201]
	v_pk_add_f32 v[98:99], v[98:99], v[202:203]
	v_pk_add_f32 v[92:93], v[92:93], v[204:205]
	v_pk_add_f32 v[94:95], v[94:95], v[206:207]
	v_cvt_pk_bf16_f32 v200, v96, v97
	v_cvt_pk_bf16_f32 v201, v98, v99
	v_cvt_pk_bf16_f32 v202, v92, v93
	v_cvt_pk_bf16_f32 v203, v94, v95
	global_store_dwordx4 v237, v[200:203], s[8:9]
	v_pk_mul_f32 v[96:97], v[96:97], v[96:97]
	v_pk_mul_f32 v[98:99], v[98:99], v[98:99]
	v_pk_fma_f32 v[96:97], v[92:93], v[92:93], v[96:97]
	v_pk_fma_f32 v[98:99], v[94:95], v[94:95], v[98:99]
	v_pk_add_f32 v[88:89], v[88:89], v[208:209]
	v_pk_add_f32 v[90:91], v[90:91], v[210:211]
	v_pk_add_f32 v[84:85], v[84:85], v[212:213]
	v_pk_add_f32 v[86:87], v[86:87], v[214:215]
	v_cvt_pk_bf16_f32 v208, v88, v89
	v_cvt_pk_bf16_f32 v209, v90, v91
	v_cvt_pk_bf16_f32 v210, v84, v85
	v_cvt_pk_bf16_f32 v211, v86, v87
	global_store_dwordx4 v237, v[208:211], s[8:9] offset:256
	v_pk_fma_f32 v[96:97], v[88:89], v[88:89], v[96:97]
	v_pk_fma_f32 v[98:99], v[90:91], v[90:91], v[98:99]
	v_pk_fma_f32 v[96:97], v[84:85], v[84:85], v[96:97]
	v_pk_fma_f32 v[98:99], v[86:87], v[86:87], v[98:99]
	v_add_u32_e32 v237, 0x8000, v237
	v_add_f32_e32 v96, v96, v97
	v_add_f32_e32 v98, v98, v99
	v_add_f32_e32 v96, v96, v98
	global_load_dwordx4 v[200:203], v236, s[6:7]
	global_load_dwordx4 v[204:207], v236, s[6:7] offset:16
	global_load_dwordx4 v[208:211], v236, s[6:7] offset:512
	global_load_dwordx4 v[212:215], v236, s[6:7] offset:528
	v_add_u32_e32 v236, 0x10000, v236
	s_waitcnt vmcnt(18)
	v_pk_add_f32 v[80:81], v[80:81], v[216:217]
	v_pk_add_f32 v[82:83], v[82:83], v[218:219]
	v_pk_add_f32 v[76:77], v[76:77], v[220:221]
	v_pk_add_f32 v[78:79], v[78:79], v[222:223]
	v_cvt_pk_bf16_f32 v216, v80, v81
	v_cvt_pk_bf16_f32 v217, v82, v83
	v_cvt_pk_bf16_f32 v218, v76, v77
	v_cvt_pk_bf16_f32 v219, v78, v79
	global_store_dwordx4 v237, v[216:219], s[8:9]
	v_pk_mul_f32 v[80:81], v[80:81], v[80:81]
	v_pk_mul_f32 v[82:83], v[82:83], v[82:83]
	v_pk_fma_f32 v[80:81], v[76:77], v[76:77], v[80:81]
	v_pk_fma_f32 v[82:83], v[78:79], v[78:79], v[82:83]
	v_pk_add_f32 v[72:73], v[72:73], v[224:225]
	v_pk_add_f32 v[74:75], v[74:75], v[226:227]
	v_pk_add_f32 v[68:69], v[68:69], v[228:229]
	v_pk_add_f32 v[70:71], v[70:71], v[230:231]
	v_cvt_pk_bf16_f32 v224, v72, v73
	v_cvt_pk_bf16_f32 v225, v74, v75
	v_cvt_pk_bf16_f32 v226, v68, v69
	v_cvt_pk_bf16_f32 v227, v70, v71
	global_store_dwordx4 v237, v[224:227], s[8:9] offset:256
	v_pk_fma_f32 v[80:81], v[72:73], v[72:73], v[80:81]
	v_pk_fma_f32 v[82:83], v[74:75], v[74:75], v[82:83]
	v_pk_fma_f32 v[80:81], v[68:69], v[68:69], v[80:81]
	v_pk_fma_f32 v[82:83], v[70:71], v[70:71], v[82:83]
	v_add_u32_e32 v237, 0x28000, v237
	v_add_f32_e32 v80, v80, v81
	v_add_f32_e32 v82, v82, v83
	v_add_f32_e32 v80, v80, v82
	global_load_dwordx4 v[216:219], v236, s[6:7]
	global_load_dwordx4 v[220:223], v236, s[6:7] offset:16
	global_load_dwordx4 v[224:227], v236, s[6:7] offset:512
	global_load_dwordx4 v[228:231], v236, s[6:7] offset:528
	s_waitcnt vmcnt(18)
	v_pk_add_f32 v[64:65], v[64:65], v[132:133]
	v_pk_add_f32 v[66:67], v[66:67], v[134:135]
	v_pk_add_f32 v[60:61], v[60:61], v[136:137]
	v_pk_add_f32 v[62:63], v[62:63], v[138:139]
	v_cvt_pk_bf16_f32 v132, v64, v65
	v_cvt_pk_bf16_f32 v133, v66, v67
	v_cvt_pk_bf16_f32 v134, v60, v61
	v_cvt_pk_bf16_f32 v135, v62, v63
	global_store_dwordx4 v237, v[132:135], s[8:9]
	v_pk_mul_f32 v[64:65], v[64:65], v[64:65]
	v_pk_mul_f32 v[66:67], v[66:67], v[66:67]
	v_pk_fma_f32 v[64:65], v[60:61], v[60:61], v[64:65]
	v_pk_fma_f32 v[66:67], v[62:63], v[62:63], v[66:67]
	v_pk_add_f32 v[56:57], v[56:57], v[148:149]
	v_pk_add_f32 v[58:59], v[58:59], v[150:151]
	v_pk_add_f32 v[52:53], v[52:53], v[152:153]
	v_pk_add_f32 v[54:55], v[54:55], v[154:155]
	v_cvt_pk_bf16_f32 v148, v56, v57
	v_cvt_pk_bf16_f32 v149, v58, v59
	v_cvt_pk_bf16_f32 v150, v52, v53
	v_cvt_pk_bf16_f32 v151, v54, v55
	global_store_dwordx4 v237, v[148:151], s[8:9] offset:256
	v_pk_fma_f32 v[64:65], v[56:57], v[56:57], v[64:65]
	v_pk_fma_f32 v[66:67], v[58:59], v[58:59], v[66:67]
	v_pk_fma_f32 v[64:65], v[52:53], v[52:53], v[64:65]
	v_pk_fma_f32 v[66:67], v[54:55], v[54:55], v[66:67]
	v_add_u32_e32 v237, 0x8000, v237
	v_add_f32_e32 v64, v64, v65
	v_add_f32_e32 v66, v66, v67
	v_add_f32_e32 v64, v64, v66
	s_waitcnt vmcnt(14)
	v_pk_add_f32 v[48:49], v[48:49], v[178:179]
	v_pk_add_f32 v[50:51], v[50:51], v[180:181]
	v_pk_add_f32 v[44:45], v[44:45], v[182:183]
	v_pk_add_f32 v[46:47], v[46:47], v[184:185]
	v_cvt_pk_bf16_f32 v178, v48, v49
	v_cvt_pk_bf16_f32 v179, v50, v51
	v_cvt_pk_bf16_f32 v180, v44, v45
	v_cvt_pk_bf16_f32 v181, v46, v47
	global_store_dwordx4 v237, v[178:181], s[8:9]
	v_pk_mul_f32 v[48:49], v[48:49], v[48:49]
	v_pk_mul_f32 v[50:51], v[50:51], v[50:51]
	v_pk_fma_f32 v[48:49], v[44:45], v[44:45], v[48:49]
	v_pk_fma_f32 v[50:51], v[46:47], v[46:47], v[50:51]
	v_pk_add_f32 v[40:41], v[40:41], v[186:187]
	v_pk_add_f32 v[42:43], v[42:43], v[188:189]
	v_pk_add_f32 v[36:37], v[36:37], v[190:191]
	v_pk_add_f32 v[38:39], v[38:39], v[192:193]
	v_cvt_pk_bf16_f32 v186, v40, v41
	v_cvt_pk_bf16_f32 v187, v42, v43
	v_cvt_pk_bf16_f32 v188, v36, v37
	v_cvt_pk_bf16_f32 v189, v38, v39
	global_store_dwordx4 v237, v[186:189], s[8:9] offset:256
	v_pk_fma_f32 v[48:49], v[40:41], v[40:41], v[48:49]
	v_pk_fma_f32 v[50:51], v[42:43], v[42:43], v[50:51]
	v_pk_fma_f32 v[48:49], v[36:37], v[36:37], v[48:49]
	v_pk_fma_f32 v[50:51], v[38:39], v[38:39], v[50:51]
	v_add_u32_e32 v237, 0x8000, v237
	v_add_f32_e32 v48, v48, v49
	v_add_f32_e32 v50, v50, v51
	v_add_f32_e32 v48, v48, v50
	s_waitcnt vmcnt(10)
	v_pk_add_f32 v[32:33], v[32:33], v[200:201]
	v_pk_add_f32 v[34:35], v[34:35], v[202:203]
	v_pk_add_f32 v[28:29], v[28:29], v[204:205]
	v_pk_add_f32 v[30:31], v[30:31], v[206:207]
	v_cvt_pk_bf16_f32 v200, v32, v33
	v_cvt_pk_bf16_f32 v201, v34, v35
	v_cvt_pk_bf16_f32 v202, v28, v29
	v_cvt_pk_bf16_f32 v203, v30, v31
	global_store_dwordx4 v237, v[200:203], s[8:9]
	v_pk_mul_f32 v[32:33], v[32:33], v[32:33]
	v_pk_mul_f32 v[34:35], v[34:35], v[34:35]
	v_pk_fma_f32 v[32:33], v[28:29], v[28:29], v[32:33]
	v_pk_fma_f32 v[34:35], v[30:31], v[30:31], v[34:35]
	v_pk_add_f32 v[24:25], v[24:25], v[208:209]
	v_pk_add_f32 v[26:27], v[26:27], v[210:211]
	v_pk_add_f32 v[20:21], v[20:21], v[212:213]
	v_pk_add_f32 v[22:23], v[22:23], v[214:215]
	v_cvt_pk_bf16_f32 v208, v24, v25
	v_cvt_pk_bf16_f32 v209, v26, v27
	v_cvt_pk_bf16_f32 v210, v20, v21
	v_cvt_pk_bf16_f32 v211, v22, v23
	global_store_dwordx4 v237, v[208:211], s[8:9] offset:256
	v_pk_fma_f32 v[32:33], v[24:25], v[24:25], v[32:33]
	v_pk_fma_f32 v[34:35], v[26:27], v[26:27], v[34:35]
	v_pk_fma_f32 v[32:33], v[20:21], v[20:21], v[32:33]
	v_pk_fma_f32 v[34:35], v[22:23], v[22:23], v[34:35]
	v_add_u32_e32 v237, 0x8000, v237
	v_add_f32_e32 v32, v32, v33
	v_add_f32_e32 v34, v34, v35
	v_add_f32_e32 v32, v32, v34
	s_waitcnt vmcnt(6)
	v_pk_add_f32 v[16:17], v[16:17], v[216:217]
	v_pk_add_f32 v[18:19], v[18:19], v[218:219]
	v_pk_add_f32 v[12:13], v[12:13], v[220:221]
	v_pk_add_f32 v[14:15], v[14:15], v[222:223]
	v_cvt_pk_bf16_f32 v216, v16, v17
	v_cvt_pk_bf16_f32 v217, v18, v19
	v_cvt_pk_bf16_f32 v218, v12, v13
	v_cvt_pk_bf16_f32 v219, v14, v15
	global_store_dwordx4 v237, v[216:219], s[8:9]
	v_pk_mul_f32 v[16:17], v[16:17], v[16:17]
	v_pk_mul_f32 v[18:19], v[18:19], v[18:19]
	v_pk_fma_f32 v[16:17], v[12:13], v[12:13], v[16:17]
	v_pk_fma_f32 v[18:19], v[14:15], v[14:15], v[18:19]
	v_pk_add_f32 v[8:9], v[8:9], v[224:225]
	v_pk_add_f32 v[10:11], v[10:11], v[226:227]
	v_pk_add_f32 v[4:5], v[4:5], v[228:229]
	v_pk_add_f32 v[6:7], v[6:7], v[230:231]
	v_cvt_pk_bf16_f32 v224, v8, v9
	v_cvt_pk_bf16_f32 v225, v10, v11
	v_cvt_pk_bf16_f32 v226, v4, v5
	v_cvt_pk_bf16_f32 v227, v6, v7
	global_store_dwordx4 v237, v[224:227], s[8:9] offset:256
	v_pk_fma_f32 v[16:17], v[8:9], v[8:9], v[16:17]
	v_pk_fma_f32 v[18:19], v[10:11], v[10:11], v[18:19]
	v_pk_fma_f32 v[16:17], v[4:5], v[4:5], v[16:17]
	v_pk_fma_f32 v[18:19], v[6:7], v[6:7], v[18:19]
	v_add_f32_e32 v16, v16, v17
	v_add_f32_e32 v18, v18, v19
	v_add_f32_e32 v16, v16, v18
	ds_bpermute_b32 v129, v239, v128
	ds_bpermute_b32 v113, v239, v112
	ds_bpermute_b32 v97, v239, v96
	ds_bpermute_b32 v81, v239, v80
	ds_bpermute_b32 v65, v239, v64
	ds_bpermute_b32 v49, v239, v48
	ds_bpermute_b32 v33, v239, v32
	ds_bpermute_b32 v17, v239, v16
	s_waitcnt lgkmcnt(0)
	v_add_f32_e32 v128, v128, v129
	v_add_f32_e32 v112, v112, v113
	v_add_f32_e32 v96, v96, v97
	v_add_f32_e32 v80, v80, v81
	v_add_f32_e32 v64, v64, v65
	v_add_f32_e32 v48, v48, v49
	v_add_f32_e32 v32, v32, v33
	v_add_f32_e32 v16, v16, v17
	ds_bpermute_b32 v129, v172, v128
	ds_bpermute_b32 v113, v172, v112
	ds_bpermute_b32 v97, v172, v96
	ds_bpermute_b32 v81, v172, v80
	ds_bpermute_b32 v65, v172, v64
	ds_bpermute_b32 v49, v172, v48
	ds_bpermute_b32 v33, v172, v32
	ds_bpermute_b32 v17, v172, v16
	s_waitcnt lgkmcnt(0)
	s_and_saveexec_b64 s[14:15], s[0:1]
	v_add_f32_e32 v128, v128, v129
	v_add_f32_e32 v112, v112, v113
	v_add_f32_e32 v96, v96, v97
	v_add_f32_e32 v80, v80, v81
	v_add_f32_e32 v64, v64, v65
	v_add_f32_e32 v48, v48, v49
	v_add_f32_e32 v32, v32, v33
	v_add_f32_e32 v16, v16, v17
	global_atomic_add_f32 v238, v128, s[10:11]
	global_atomic_add_f32 v238, v112, s[10:11] offset:64
	global_atomic_add_f32 v238, v96, s[10:11] offset:128
	global_atomic_add_f32 v238, v80, s[10:11] offset:192
	global_atomic_add_f32 v238, v64, s[10:11] offset:512
	global_atomic_add_f32 v238, v48, s[10:11] offset:576
	global_atomic_add_f32 v238, v32, s[10:11] offset:640
	global_atomic_add_f32 v238, v16, s[10:11] offset:704
	s_branch .LBB0_879
.Lg2_epi_bf16:
	v_lshl_add_u32 v238, s77, 8, v174
	v_lshl_or_b32 v237, s76, 8, v176
	v_lshl_add_u32 v236, v238, 10, v237
	v_lshlrev_b32_e32 v236, 1, v236
	v_mov_b32_e32 v237, v236
	v_lshlrev_b32_e32 v238, 2, v238
	global_load_dwordx4 v[132:135], v236, s[8:9]
	global_load_dwordx4 v[136:139], v236, s[8:9] offset:256
	v_add_u32_e32 v236, 0x8000, v236
	global_load_dwordx4 v[148:151], v236, s[8:9]
	global_load_dwordx4 v[152:155], v236, s[8:9] offset:256
	v_add_u32_e32 v236, 0x8000, v236
	global_load_dwordx4 v[178:181], v236, s[8:9]
	global_load_dwordx4 v[182:185], v236, s[8:9] offset:256
	v_add_u32_e32 v236, 0x8000, v236
	global_load_dwordx4 v[186:189], v236, s[8:9]
	global_load_dwordx4 v[190:193], v236, s[8:9] offset:256
	v_add_u32_e32 v236, 0x28000, v236
	global_load_dwordx4 v[200:203], v236, s[8:9]
	global_load_dwordx4 v[204:207], v236, s[8:9] offset:256
	v_add_u32_e32 v236, 0x8000, v236
	global_load_dwordx4 v[208:211], v236, s[8:9]
	global_load_dwordx4 v[212:215], v236, s[8:9] offset:256
	v_add_u32_e32 v236, 0x8000, v236
	global_load_dwordx4 v[216:219], v236, s[8:9]
	global_load_dwordx4 v[220:223], v236, s[8:9] offset:256
	v_add_u32_e32 v236, 0x8000, v236
	global_load_dwordx4 v[224:227], v236, s[8:9]
	global_load_dwordx4 v[228:231], v236, s[8:9] offset:256
	v_xor_b32_e32 v239, 16, v197
	v_xor_b32_e32 v172, 32, v197
	v_lshlrev_b32_e32 v239, 2, v239
	v_lshlrev_b32_e32 v172, 2, v172
	s_waitcnt vmcnt(14)
	v_lshlrev_b32_e32 v232, 16, v132
	v_and_b32_e32 v233, 0xffff0000, v132
	v_lshlrev_b32_e32 v234, 16, v133
	v_and_b32_e32 v235, 0xffff0000, v133
	v_lshlrev_b32_e32 v132, 16, v134
	v_and_b32_e32 v133, 0xffff0000, v134
	v_lshlrev_b32_e32 v134, 16, v135
	v_and_b32_e32 v135, 0xffff0000, v135
	v_pk_add_f32 v[128:129], v[128:129], v[232:233]
	v_pk_add_f32 v[130:131], v[130:131], v[234:235]
	v_pk_add_f32 v[124:125], v[124:125], v[132:133]
	v_pk_add_f32 v[126:127], v[126:127], v[134:135]
	v_cvt_pk_bf16_f32 v132, v128, v129
	v_cvt_pk_bf16_f32 v133, v130, v131
	v_cvt_pk_bf16_f32 v134, v124, v125
	v_cvt_pk_bf16_f32 v135, v126, v127
	global_store_dwordx4 v237, v[132:135], s[8:9]
	v_pk_mul_f32 v[128:129], v[128:129], v[128:129]
	v_pk_mul_f32 v[130:131], v[130:131], v[130:131]
	v_pk_fma_f32 v[128:129], v[124:125], v[124:125], v[128:129]
	v_pk_fma_f32 v[130:131], v[126:127], v[126:127], v[130:131]
	v_lshlrev_b32_e32 v232, 16, v136
	v_and_b32_e32 v233, 0xffff0000, v136
	v_lshlrev_b32_e32 v234, 16, v137
	v_and_b32_e32 v235, 0xffff0000, v137
	v_lshlrev_b32_e32 v136, 16, v138
	v_and_b32_e32 v137, 0xffff0000, v138
	v_lshlrev_b32_e32 v138, 16, v139
	v_and_b32_e32 v139, 0xffff0000, v139
	v_pk_add_f32 v[120:121], v[120:121], v[232:233]
	v_pk_add_f32 v[122:123], v[122:123], v[234:235]
	v_pk_add_f32 v[116:117], v[116:117], v[136:137]
	v_pk_add_f32 v[118:119], v[118:119], v[138:139]
	v_cvt_pk_bf16_f32 v136, v120, v121
	v_cvt_pk_bf16_f32 v137, v122, v123
	v_cvt_pk_bf16_f32 v138, v116, v117
	v_cvt_pk_bf16_f32 v139, v118, v119
	global_store_dwordx4 v237, v[136:139], s[8:9] offset:256
	v_pk_fma_f32 v[128:129], v[120:121], v[120:121], v[128:129]
	v_pk_fma_f32 v[130:131], v[122:123], v[122:123], v[130:131]
	v_pk_fma_f32 v[128:129], v[116:117], v[116:117], v[128:129]
	v_pk_fma_f32 v[130:131], v[118:119], v[118:119], v[130:131]
	v_add_u32_e32 v237, 0x8000, v237
	v_add_f32_e32 v128, v128, v129
	v_add_f32_e32 v130, v130, v131
	v_add_f32_e32 v128, v128, v130
	s_waitcnt vmcnt(14)
	v_lshlrev_b32_e32 v232, 16, v148
	v_and_b32_e32 v233, 0xffff0000, v148
	v_lshlrev_b32_e32 v234, 16, v149
	v_and_b32_e32 v235, 0xffff0000, v149
	v_lshlrev_b32_e32 v148, 16, v150
	v_and_b32_e32 v149, 0xffff0000, v150
	v_lshlrev_b32_e32 v150, 16, v151
	v_and_b32_e32 v151, 0xffff0000, v151
	v_pk_add_f32 v[112:113], v[112:113], v[232:233]
	v_pk_add_f32 v[114:115], v[114:115], v[234:235]
	v_pk_add_f32 v[108:109], v[108:109], v[148:149]
	v_pk_add_f32 v[110:111], v[110:111], v[150:151]
	v_cvt_pk_bf16_f32 v148, v112, v113
	v_cvt_pk_bf16_f32 v149, v114, v115
	v_cvt_pk_bf16_f32 v150, v108, v109
	v_cvt_pk_bf16_f32 v151, v110, v111
	global_store_dwordx4 v237, v[148:151], s[8:9]
	v_pk_mul_f32 v[112:113], v[112:113], v[112:113]
	v_pk_mul_f32 v[114:115], v[114:115], v[114:115]
	v_pk_fma_f32 v[112:113], v[108:109], v[108:109], v[112:113]
	v_pk_fma_f32 v[114:115], v[110:111], v[110:111], v[114:115]
	v_lshlrev_b32_e32 v232, 16, v152
	v_and_b32_e32 v233, 0xffff0000, v152
	v_lshlrev_b32_e32 v234, 16, v153
	v_and_b32_e32 v235, 0xffff0000, v153
	v_lshlrev_b32_e32 v152, 16, v154
	v_and_b32_e32 v153, 0xffff0000, v154
	v_lshlrev_b32_e32 v154, 16, v155
	v_and_b32_e32 v155, 0xffff0000, v155
	v_pk_add_f32 v[104:105], v[104:105], v[232:233]
	v_pk_add_f32 v[106:107], v[106:107], v[234:235]
	v_pk_add_f32 v[100:101], v[100:101], v[152:153]
	v_pk_add_f32 v[102:103], v[102:103], v[154:155]
	v_cvt_pk_bf16_f32 v152, v104, v105
	v_cvt_pk_bf16_f32 v153, v106, v107
	v_cvt_pk_bf16_f32 v154, v100, v101
	v_cvt_pk_bf16_f32 v155, v102, v103
	global_store_dwordx4 v237, v[152:155], s[8:9] offset:256
	v_pk_fma_f32 v[112:113], v[104:105], v[104:105], v[112:113]
	v_pk_fma_f32 v[114:115], v[106:107], v[106:107], v[114:115]
	v_pk_fma_f32 v[112:113], v[100:101], v[100:101], v[112:113]
	v_pk_fma_f32 v[114:115], v[102:103], v[102:103], v[114:115]
	v_add_u32_e32 v237, 0x8000, v237
	v_add_f32_e32 v112, v112, v113
	v_add_f32_e32 v114, v114, v115
	v_add_f32_e32 v112, v112, v114
	s_waitcnt vmcnt(14)
	v_lshlrev_b32_e32 v232, 16, v178
	v_and_b32_e32 v233, 0xffff0000, v178
	v_lshlrev_b32_e32 v234, 16, v179
	v_and_b32_e32 v235, 0xffff0000, v179
	v_lshlrev_b32_e32 v178, 16, v180
	v_and_b32_e32 v179, 0xffff0000, v180
	v_lshlrev_b32_e32 v180, 16, v181
	v_and_b32_e32 v181, 0xffff0000, v181
	v_pk_add_f32 v[96:97], v[96:97], v[232:233]
	v_pk_add_f32 v[98:99], v[98:99], v[234:235]
	v_pk_add_f32 v[92:93], v[92:93], v[178:179]
	v_pk_add_f32 v[94:95], v[94:95], v[180:181]
	v_cvt_pk_bf16_f32 v178, v96, v97
	v_cvt_pk_bf16_f32 v179, v98, v99
	v_cvt_pk_bf16_f32 v180, v92, v93
	v_cvt_pk_bf16_f32 v181, v94, v95
	global_store_dwordx4 v237, v[178:181], s[8:9]
	v_pk_mul_f32 v[96:97], v[96:97], v[96:97]
	v_pk_mul_f32 v[98:99], v[98:99], v[98:99]
	v_pk_fma_f32 v[96:97], v[92:93], v[92:93], v[96:97]
	v_pk_fma_f32 v[98:99], v[94:95], v[94:95], v[98:99]
	v_lshlrev_b32_e32 v232, 16, v182
	v_and_b32_e32 v233, 0xffff0000, v182
	v_lshlrev_b32_e32 v234, 16, v183
	v_and_b32_e32 v235, 0xffff0000, v183
	v_lshlrev_b32_e32 v182, 16, v184
	v_and_b32_e32 v183, 0xffff0000, v184
	v_lshlrev_b32_e32 v184, 16, v185
	v_and_b32_e32 v185, 0xffff0000, v185
	v_pk_add_f32 v[88:89], v[88:89], v[232:233]
	v_pk_add_f32 v[90:91], v[90:91], v[234:235]
	v_pk_add_f32 v[84:85], v[84:85], v[182:183]
	v_pk_add_f32 v[86:87], v[86:87], v[184:185]
	v_cvt_pk_bf16_f32 v182, v88, v89
	v_cvt_pk_bf16_f32 v183, v90, v91
	v_cvt_pk_bf16_f32 v184, v84, v85
	v_cvt_pk_bf16_f32 v185, v86, v87
	global_store_dwordx4 v237, v[182:185], s[8:9] offset:256
	v_pk_fma_f32 v[96:97], v[88:89], v[88:89], v[96:97]
	v_pk_fma_f32 v[98:99], v[90:91], v[90:91], v[98:99]
	v_pk_fma_f32 v[96:97], v[84:85], v[84:85], v[96:97]
	v_pk_fma_f32 v[98:99], v[86:87], v[86:87], v[98:99]
	v_add_u32_e32 v237, 0x8000, v237
	v_add_f32_e32 v96, v96, v97
	v_add_f32_e32 v98, v98, v99
	v_add_f32_e32 v96, v96, v98
	s_waitcnt vmcnt(14)
	v_lshlrev_b32_e32 v232, 16, v186
	v_and_b32_e32 v233, 0xffff0000, v186
	v_lshlrev_b32_e32 v234, 16, v187
	v_and_b32_e32 v235, 0xffff0000, v187
	v_lshlrev_b32_e32 v186, 16, v188
	v_and_b32_e32 v187, 0xffff0000, v188
	v_lshlrev_b32_e32 v188, 16, v189
	v_and_b32_e32 v189, 0xffff0000, v189
	v_pk_add_f32 v[80:81], v[80:81], v[232:233]
	v_pk_add_f32 v[82:83], v[82:83], v[234:235]
	v_pk_add_f32 v[76:77], v[76:77], v[186:187]
	v_pk_add_f32 v[78:79], v[78:79], v[188:189]
	v_cvt_pk_bf16_f32 v186, v80, v81
	v_cvt_pk_bf16_f32 v187, v82, v83
	v_cvt_pk_bf16_f32 v188, v76, v77
	v_cvt_pk_bf16_f32 v189, v78, v79
	global_store_dwordx4 v237, v[186:189], s[8:9]
	v_pk_mul_f32 v[80:81], v[80:81], v[80:81]
	v_pk_mul_f32 v[82:83], v[82:83], v[82:83]
	v_pk_fma_f32 v[80:81], v[76:77], v[76:77], v[80:81]
	v_pk_fma_f32 v[82:83], v[78:79], v[78:79], v[82:83]
	v_lshlrev_b32_e32 v232, 16, v190
	v_and_b32_e32 v233, 0xffff0000, v190
	v_lshlrev_b32_e32 v234, 16, v191
	v_and_b32_e32 v235, 0xffff0000, v191
	v_lshlrev_b32_e32 v190, 16, v192
	v_and_b32_e32 v191, 0xffff0000, v192
	v_lshlrev_b32_e32 v192, 16, v193
	v_and_b32_e32 v193, 0xffff0000, v193
	v_pk_add_f32 v[72:73], v[72:73], v[232:233]
	v_pk_add_f32 v[74:75], v[74:75], v[234:235]
	v_pk_add_f32 v[68:69], v[68:69], v[190:191]
	v_pk_add_f32 v[70:71], v[70:71], v[192:193]
	v_cvt_pk_bf16_f32 v190, v72, v73
	v_cvt_pk_bf16_f32 v191, v74, v75
	v_cvt_pk_bf16_f32 v192, v68, v69
	v_cvt_pk_bf16_f32 v193, v70, v71
	global_store_dwordx4 v237, v[190:193], s[8:9] offset:256
	v_pk_fma_f32 v[80:81], v[72:73], v[72:73], v[80:81]
	v_pk_fma_f32 v[82:83], v[74:75], v[74:75], v[82:83]
	v_pk_fma_f32 v[80:81], v[68:69], v[68:69], v[80:81]
	v_pk_fma_f32 v[82:83], v[70:71], v[70:71], v[82:83]
	v_add_u32_e32 v237, 0x28000, v237
	v_add_f32_e32 v80, v80, v81
	v_add_f32_e32 v82, v82, v83
	v_add_f32_e32 v80, v80, v82
	s_waitcnt vmcnt(14)
	v_lshlrev_b32_e32 v232, 16, v200
	v_and_b32_e32 v233, 0xffff0000, v200
	v_lshlrev_b32_e32 v234, 16, v201
	v_and_b32_e32 v235, 0xffff0000, v201
	v_lshlrev_b32_e32 v200, 16, v202
	v_and_b32_e32 v201, 0xffff0000, v202
	v_lshlrev_b32_e32 v202, 16, v203
	v_and_b32_e32 v203, 0xffff0000, v203
	v_pk_add_f32 v[64:65], v[64:65], v[232:233]
	v_pk_add_f32 v[66:67], v[66:67], v[234:235]
	v_pk_add_f32 v[60:61], v[60:61], v[200:201]
	v_pk_add_f32 v[62:63], v[62:63], v[202:203]
	v_cvt_pk_bf16_f32 v200, v64, v65
	v_cvt_pk_bf16_f32 v201, v66, v67
	v_cvt_pk_bf16_f32 v202, v60, v61
	v_cvt_pk_bf16_f32 v203, v62, v63
	global_store_dwordx4 v237, v[200:203], s[8:9]
	v_pk_mul_f32 v[64:65], v[64:65], v[64:65]
	v_pk_mul_f32 v[66:67], v[66:67], v[66:67]
	v_pk_fma_f32 v[64:65], v[60:61], v[60:61], v[64:65]
	v_pk_fma_f32 v[66:67], v[62:63], v[62:63], v[66:67]
	v_lshlrev_b32_e32 v232, 16, v204
	v_and_b32_e32 v233, 0xffff0000, v204
	v_lshlrev_b32_e32 v234, 16, v205
	v_and_b32_e32 v235, 0xffff0000, v205
	v_lshlrev_b32_e32 v204, 16, v206
	v_and_b32_e32 v205, 0xffff0000, v206
	v_lshlrev_b32_e32 v206, 16, v207
	v_and_b32_e32 v207, 0xffff0000, v207
	v_pk_add_f32 v[56:57], v[56:57], v[232:233]
	v_pk_add_f32 v[58:59], v[58:59], v[234:235]
	v_pk_add_f32 v[52:53], v[52:53], v[204:205]
	v_pk_add_f32 v[54:55], v[54:55], v[206:207]
	v_cvt_pk_bf16_f32 v204, v56, v57
	v_cvt_pk_bf16_f32 v205, v58, v59
	v_cvt_pk_bf16_f32 v206, v52, v53
	v_cvt_pk_bf16_f32 v207, v54, v55
	global_store_dwordx4 v237, v[204:207], s[8:9] offset:256
	v_pk_fma_f32 v[64:65], v[56:57], v[56:57], v[64:65]
	v_pk_fma_f32 v[66:67], v[58:59], v[58:59], v[66:67]
	v_pk_fma_f32 v[64:65], v[52:53], v[52:53], v[64:65]
	v_pk_fma_f32 v[66:67], v[54:55], v[54:55], v[66:67]
	v_add_u32_e32 v237, 0x8000, v237
	v_add_f32_e32 v64, v64, v65
	v_add_f32_e32 v66, v66, v67
	v_add_f32_e32 v64, v64, v66
	s_waitcnt vmcnt(14)
	v_lshlrev_b32_e32 v232, 16, v208
	v_and_b32_e32 v233, 0xffff0000, v208
	v_lshlrev_b32_e32 v234, 16, v209
	v_and_b32_e32 v235, 0xffff0000, v209
	v_lshlrev_b32_e32 v208, 16, v210
	v_and_b32_e32 v209, 0xffff0000, v210
	v_lshlrev_b32_e32 v210, 16, v211
	v_and_b32_e32 v211, 0xffff0000, v211
	v_pk_add_f32 v[48:49], v[48:49], v[232:233]
	v_pk_add_f32 v[50:51], v[50:51], v[234:235]
	v_pk_add_f32 v[44:45], v[44:45], v[208:209]
	v_pk_add_f32 v[46:47], v[46:47], v[210:211]
	v_cvt_pk_bf16_f32 v208, v48, v49
	v_cvt_pk_bf16_f32 v209, v50, v51
	v_cvt_pk_bf16_f32 v210, v44, v45
	v_cvt_pk_bf16_f32 v211, v46, v47
	global_store_dwordx4 v237, v[208:211], s[8:9]
	v_pk_mul_f32 v[48:49], v[48:49], v[48:49]
	v_pk_mul_f32 v[50:51], v[50:51], v[50:51]
	v_pk_fma_f32 v[48:49], v[44:45], v[44:45], v[48:49]
	v_pk_fma_f32 v[50:51], v[46:47], v[46:47], v[50:51]
	v_lshlrev_b32_e32 v232, 16, v212
	v_and_b32_e32 v233, 0xffff0000, v212
	v_lshlrev_b32_e32 v234, 16, v213
	v_and_b32_e32 v235, 0xffff0000, v213
	v_lshlrev_b32_e32 v212, 16, v214
	v_and_b32_e32 v213, 0xffff0000, v214
	v_lshlrev_b32_e32 v214, 16, v215
	v_and_b32_e32 v215, 0xffff0000, v215
	v_pk_add_f32 v[40:41], v[40:41], v[232:233]
	v_pk_add_f32 v[42:43], v[42:43], v[234:235]
	v_pk_add_f32 v[36:37], v[36:37], v[212:213]
	v_pk_add_f32 v[38:39], v[38:39], v[214:215]
	v_cvt_pk_bf16_f32 v212, v40, v41
	v_cvt_pk_bf16_f32 v213, v42, v43
	v_cvt_pk_bf16_f32 v214, v36, v37
	v_cvt_pk_bf16_f32 v215, v38, v39
	global_store_dwordx4 v237, v[212:215], s[8:9] offset:256
	v_pk_fma_f32 v[48:49], v[40:41], v[40:41], v[48:49]
	v_pk_fma_f32 v[50:51], v[42:43], v[42:43], v[50:51]
	v_pk_fma_f32 v[48:49], v[36:37], v[36:37], v[48:49]
	v_pk_fma_f32 v[50:51], v[38:39], v[38:39], v[50:51]
	v_add_u32_e32 v237, 0x8000, v237
	v_add_f32_e32 v48, v48, v49
	v_add_f32_e32 v50, v50, v51
	v_add_f32_e32 v48, v48, v50
	s_waitcnt vmcnt(14)
	v_lshlrev_b32_e32 v232, 16, v216
	v_and_b32_e32 v233, 0xffff0000, v216
	v_lshlrev_b32_e32 v234, 16, v217
	v_and_b32_e32 v235, 0xffff0000, v217
	v_lshlrev_b32_e32 v216, 16, v218
	v_and_b32_e32 v217, 0xffff0000, v218
	v_lshlrev_b32_e32 v218, 16, v219
	v_and_b32_e32 v219, 0xffff0000, v219
	v_pk_add_f32 v[32:33], v[32:33], v[232:233]
	v_pk_add_f32 v[34:35], v[34:35], v[234:235]
	v_pk_add_f32 v[28:29], v[28:29], v[216:217]
	v_pk_add_f32 v[30:31], v[30:31], v[218:219]
	v_cvt_pk_bf16_f32 v216, v32, v33
	v_cvt_pk_bf16_f32 v217, v34, v35
	v_cvt_pk_bf16_f32 v218, v28, v29
	v_cvt_pk_bf16_f32 v219, v30, v31
	global_store_dwordx4 v237, v[216:219], s[8:9]
	v_pk_mul_f32 v[32:33], v[32:33], v[32:33]
	v_pk_mul_f32 v[34:35], v[34:35], v[34:35]
	v_pk_fma_f32 v[32:33], v[28:29], v[28:29], v[32:33]
	v_pk_fma_f32 v[34:35], v[30:31], v[30:31], v[34:35]
	v_lshlrev_b32_e32 v232, 16, v220
	v_and_b32_e32 v233, 0xffff0000, v220
	v_lshlrev_b32_e32 v234, 16, v221
	v_and_b32_e32 v235, 0xffff0000, v221
	v_lshlrev_b32_e32 v220, 16, v222
	v_and_b32_e32 v221, 0xffff0000, v222
	v_lshlrev_b32_e32 v222, 16, v223
	v_and_b32_e32 v223, 0xffff0000, v223
	v_pk_add_f32 v[24:25], v[24:25], v[232:233]
	v_pk_add_f32 v[26:27], v[26:27], v[234:235]
	v_pk_add_f32 v[20:21], v[20:21], v[220:221]
	v_pk_add_f32 v[22:23], v[22:23], v[222:223]
	v_cvt_pk_bf16_f32 v220, v24, v25
	v_cvt_pk_bf16_f32 v221, v26, v27
	v_cvt_pk_bf16_f32 v222, v20, v21
	v_cvt_pk_bf16_f32 v223, v22, v23
	global_store_dwordx4 v237, v[220:223], s[8:9] offset:256
	v_pk_fma_f32 v[32:33], v[24:25], v[24:25], v[32:33]
	v_pk_fma_f32 v[34:35], v[26:27], v[26:27], v[34:35]
	v_pk_fma_f32 v[32:33], v[20:21], v[20:21], v[32:33]
	v_pk_fma_f32 v[34:35], v[22:23], v[22:23], v[34:35]
	v_add_u32_e32 v237, 0x8000, v237
	v_add_f32_e32 v32, v32, v33
	v_add_f32_e32 v34, v34, v35
	v_add_f32_e32 v32, v32, v34
	s_waitcnt vmcnt(14)
	v_lshlrev_b32_e32 v232, 16, v224
	v_and_b32_e32 v233, 0xffff0000, v224
	v_lshlrev_b32_e32 v234, 16, v225
	v_and_b32_e32 v235, 0xffff0000, v225
	v_lshlrev_b32_e32 v224, 16, v226
	v_and_b32_e32 v225, 0xffff0000, v226
	v_lshlrev_b32_e32 v226, 16, v227
	v_and_b32_e32 v227, 0xffff0000, v227
	v_pk_add_f32 v[16:17], v[16:17], v[232:233]
	v_pk_add_f32 v[18:19], v[18:19], v[234:235]
	v_pk_add_f32 v[12:13], v[12:13], v[224:225]
	v_pk_add_f32 v[14:15], v[14:15], v[226:227]
	v_cvt_pk_bf16_f32 v224, v16, v17
	v_cvt_pk_bf16_f32 v225, v18, v19
	v_cvt_pk_bf16_f32 v226, v12, v13
	v_cvt_pk_bf16_f32 v227, v14, v15
	global_store_dwordx4 v237, v[224:227], s[8:9]
	v_pk_mul_f32 v[16:17], v[16:17], v[16:17]
	v_pk_mul_f32 v[18:19], v[18:19], v[18:19]
	v_pk_fma_f32 v[16:17], v[12:13], v[12:13], v[16:17]
	v_pk_fma_f32 v[18:19], v[14:15], v[14:15], v[18:19]
	v_lshlrev_b32_e32 v232, 16, v228
	v_and_b32_e32 v233, 0xffff0000, v228
	v_lshlrev_b32_e32 v234, 16, v229
	v_and_b32_e32 v235, 0xffff0000, v229
	v_lshlrev_b32_e32 v228, 16, v230
	v_and_b32_e32 v229, 0xffff0000, v230
	v_lshlrev_b32_e32 v230, 16, v231
	v_and_b32_e32 v231, 0xffff0000, v231
	v_pk_add_f32 v[8:9], v[8:9], v[232:233]
	v_pk_add_f32 v[10:11], v[10:11], v[234:235]
	v_pk_add_f32 v[4:5], v[4:5], v[228:229]
	v_pk_add_f32 v[6:7], v[6:7], v[230:231]
	v_cvt_pk_bf16_f32 v228, v8, v9
	v_cvt_pk_bf16_f32 v229, v10, v11
	v_cvt_pk_bf16_f32 v230, v4, v5
	v_cvt_pk_bf16_f32 v231, v6, v7
	global_store_dwordx4 v237, v[228:231], s[8:9] offset:256
	v_pk_fma_f32 v[16:17], v[8:9], v[8:9], v[16:17]
	v_pk_fma_f32 v[18:19], v[10:11], v[10:11], v[18:19]
	v_pk_fma_f32 v[16:17], v[4:5], v[4:5], v[16:17]
	v_pk_fma_f32 v[18:19], v[6:7], v[6:7], v[18:19]
	v_add_f32_e32 v16, v16, v17
	v_add_f32_e32 v18, v18, v19
	v_add_f32_e32 v16, v16, v18
	ds_bpermute_b32 v129, v239, v128
	ds_bpermute_b32 v113, v239, v112
	ds_bpermute_b32 v97, v239, v96
	ds_bpermute_b32 v81, v239, v80
	ds_bpermute_b32 v65, v239, v64
	ds_bpermute_b32 v49, v239, v48
	ds_bpermute_b32 v33, v239, v32
	ds_bpermute_b32 v17, v239, v16
	s_waitcnt lgkmcnt(0)
	v_add_f32_e32 v128, v128, v129
	v_add_f32_e32 v112, v112, v113
	v_add_f32_e32 v96, v96, v97
	v_add_f32_e32 v80, v80, v81
	v_add_f32_e32 v64, v64, v65
	v_add_f32_e32 v48, v48, v49
	v_add_f32_e32 v32, v32, v33
	v_add_f32_e32 v16, v16, v17
	ds_bpermute_b32 v129, v172, v128
	ds_bpermute_b32 v113, v172, v112
	ds_bpermute_b32 v97, v172, v96
	ds_bpermute_b32 v81, v172, v80
	ds_bpermute_b32 v65, v172, v64
	ds_bpermute_b32 v49, v172, v48
	ds_bpermute_b32 v33, v172, v32
	ds_bpermute_b32 v17, v172, v16
	s_waitcnt lgkmcnt(0)
	s_and_saveexec_b64 s[14:15], s[0:1]
	v_add_f32_e32 v128, v128, v129
	v_add_f32_e32 v112, v112, v113
	v_add_f32_e32 v96, v96, v97
	v_add_f32_e32 v80, v80, v81
	v_add_f32_e32 v64, v64, v65
	v_add_f32_e32 v48, v48, v49
	v_add_f32_e32 v32, v32, v33
	v_add_f32_e32 v16, v16, v17
	global_atomic_add_f32 v238, v128, s[10:11]
	global_atomic_add_f32 v238, v112, s[10:11] offset:64
	global_atomic_add_f32 v238, v96, s[10:11] offset:128
	global_atomic_add_f32 v238, v80, s[10:11] offset:192
	global_atomic_add_f32 v238, v64, s[10:11] offset:512
	global_atomic_add_f32 v238, v48, s[10:11] offset:576
	global_atomic_add_f32 v238, v32, s[10:11] offset:640
	global_atomic_add_f32 v238, v16, s[10:11] offset:704
.LBB0_879:
	s_or_b64 exec, exec, s[14:15]
	s_andn2_b64 vcc, exec, s[40:41]
	s_mov_b64 s[14:15], -1
	s_cbranch_vccnz .LBB0_804
	s_andn2_b64 vcc, exec, s[4:5]
	s_cbranch_vccnz .LBB0_803
	s_barrier
	s_branch .LBB0_803
.LBB0_898:
	s_waitcnt vmcnt(0)
	v_readlane_b32 s22, v246, 0
	v_readlane_b32 s48, v243, 59
	v_readlane_b32 s38, v243, 62
	v_readlane_b32 s50, v242, 0
	v_readlane_b32 s23, v246, 1
	v_readlane_b32 s24, v243, 58
	v_readlane_b32 s49, v243, 60
	v_readlane_b32 s39, v243, 63
	v_readlane_b32 s51, v242, 1
	s_barrier
